# speedup vs baseline: 1.0468x; 1.0030x over previous
; template <int EPI> ...
;     ...
;   for (int i = 0; i < nA + nB; ++i) {
;     int pm, pn, koff;
;     bool atom;
;     tile_desc(i, pm, pn, koff, atom);
;     const int kk = atom ? Kc : K;
;     int brow = pm * 256, bcol = pn * 256;
;     void* o = outp;
;     int orow = brow;
;     if (EPI == 0) {
;       if (brow < USPLIT) {
;         o = (void*)p.out;
;       } else {
;         o = (void*)(p.ws + OFF_X);
;         orow = brow - USPLIT;
;       }
;     }
;     if (EPI == 1 && atom) {
;       o = (void*)((float*)(p.ws + OFF_PART) + (long)(koff / Kc) * (256 * DM));
;       orow = 0;
;     }
;     const char* nAb = nullptr;
;     const char* nBb = nullptr;
;     if (i + 1 < nA + nB) {
;       int pm2, pn2, koff2;
;       bool atom2;
;       tile_desc(i + 1, pm2, pn2, koff2, atom2);
;       nAb = (const char*)(A + koff2 + (long)pm2 * 256 * K);
;       nBb = (const char*)(Bt + koff2 + (long)pn2 * 256 * K);
;     }
;     gemm_tile<EPI>(A + koff, Bt + koff, kk, brow, bcol, o, orow, ldo, shm, ss_in, gain_out, atom ? nullptr : nout,
;                    ss_out, K, atom, pre, nAb, nBb);
.LBB0_103:
	s_mul_i32 s2, s59, s1
	s_add_i32 s2, s2, s34
	s_add_i32 s59, s59, 1
	s_cmp_ge_i32 s59, s33
	s_mov_b64 s[88:89], 0
	s_mov_b64 s[92:93], 0
	s_cbranch_scc1 .LBB0_105
	s_add_i32 s6, s2, s1
	s_ashr_i32 s7, s6, 31
	s_lshr_b32 s7, s7, 25
	s_add_i32 s7, s6, s7
	s_ashr_i32 s8, s7, 7
	s_lshl_b32 s8, s8, 2
	s_sub_i32 s9, s0, s8
	s_min_i32 s9, s9, 4
	s_abs_i32 s10, s9
	v_cvt_f32_u32_e32 v0, s10
	s_sub_i32 s20, 0, s10
	s_and_b32 s7, s7, 0xffffff80
	s_sub_i32 s7, s6, s7
	v_rcp_iflag_f32_e32 v0, v0
	s_abs_i32 s6, s7
	s_xor_b32 s11, s7, s9
	s_ashr_i32 s11, s11, 31
	v_mul_f32_e32 v0, 0x4f7ffffe, v0
	v_cvt_u32_f32_e32 v0, v0
	s_nop 0
	v_readfirstlane_b32 s21, v0
	s_mul_i32 s20, s20, s21
	s_mul_hi_u32 s20, s21, s20
	s_add_i32 s21, s21, s20
	s_mul_hi_u32 s20, s6, s21
	s_mul_i32 s21, s20, s10
	s_sub_i32 s6, s6, s21
	s_add_i32 s22, s20, 1
	s_sub_i32 s21, s6, s10
	s_cmp_ge_u32 s6, s10
	s_cselect_b32 s20, s22, s20
	s_cselect_b32 s6, s21, s6
	s_add_i32 s21, s20, 1
	s_cmp_ge_u32 s6, s10
	s_cselect_b32 s6, s21, s20
	s_xor_b32 s6, s6, s11
	s_sub_i32 s6, s6, s11
	s_mul_i32 s9, s6, s9
	s_sub_i32 s7, s7, s9
	s_and_b32 s9, s8, 24
	s_add_i32 s6, s6, s9
	s_and_b32 s6, s6, 31
	s_add_i32 s8, s7, s8
	s_ashr_i32 s9, s8, 31
	s_lshl_b64 s[8:9], s[8:9], 20
	s_add_u32 s88, s47, s8
	s_addc_u32 s89, s48, s9
	s_ashr_i32 s7, s6, 31
	s_lshl_b64 s[6:7], s[6:7], 20
	s_add_u32 s92, s57, s6
	s_addc_u32 s93, s58, s7
.LBB0_105:
	s_ashr_i32 s6, s2, 31
	s_lshr_b32 s6, s6, 25
	s_add_i32 s6, s2, s6
	s_ashr_i32 s7, s6, 7
	s_lshl_b32 s7, s7, 2
	s_sub_i32 s8, s0, s7
	s_min_i32 s10, s8, 4
	s_abs_i32 s11, s10
	v_cvt_f32_u32_e32 v0, s11
	s_xor_b64 s[8:9], s[12:13], -1
	s_sub_i32 s13, 0, s11
	s_and_b32 s6, s6, 0xffffff80
	v_rcp_iflag_f32_e32 v0, v0
	s_sub_i32 s2, s2, s6
	s_abs_i32 s6, s2
	s_xor_b32 s12, s2, s10
	v_mul_f32_e32 v0, 0x4f7ffffe, v0
	v_cvt_u32_f32_e32 v0, v0
	s_ashr_i32 s12, s12, 31
	v_mov_b32_e32 v134, v193
	v_readfirstlane_b32 s20, v0
	s_mul_i32 s13, s13, s20
	s_mul_hi_u32 s13, s20, s13
	s_add_i32 s20, s20, s13
	s_mul_hi_u32 s13, s6, s20
	s_mul_i32 s20, s13, s11
	s_sub_i32 s6, s6, s20
	s_add_i32 s21, s13, 1
	s_sub_i32 s20, s6, s11
	s_cmp_ge_u32 s6, s11
	s_cselect_b32 s13, s21, s13
	s_cselect_b32 s6, s20, s6
	s_add_i32 s20, s13, 1
	s_cmp_ge_u32 s6, s11
	s_cselect_b32 s6, s20, s13
	s_xor_b32 s6, s6, s12
	s_sub_i32 s6, s6, s12
	s_mul_i32 s10, s6, s10
	s_sub_i32 s2, s2, s10
	s_and_b32 s10, s7, 24
	s_add_i32 s6, s6, s10
	s_and_b32 s6, s6, 31
	s_add_i32 s7, s7, s2
	s_lshl_b32 s94, s7, 8
	s_lshl_b32 s90, s6, 8
	v_readfirstlane_b32 s2, v134
	s_lshl_b32 s2, s2, 4
	s_ashr_i32 s95, s94, 31
	s_ashr_i32 s91, s90, 31
	s_and_b32 s6, s2, 0x1c00
	s_lshl_b64 s[10:11], s[94:95], 12
	s_lshl_b64 s[12:13], s[90:91], 12
	s_cmp_lg_u32 0, -1
	s_cselect_b32 s2, 0, 0
	v_lshlrev_b32_e32 v2, 4, v134
	v_and_b32_e32 v3, 32, v134
	s_add_i32 s2, s6, s2
	v_lshrrev_b32_e32 v4, 3, v134
	v_bfe_u32 v5, v134, 2, 4
	v_bitop3_b32 v2, v2, v3, 48 bitop3:0x6c
	s_add_u32 s96, s47, s10
	v_and_or_b32 v2, v134, 64, v2
	v_and_or_b32 v3, v4, 48, v5
	s_addc_u32 s97, s48, s11
	v_ashrrev_i32_e32 v0, 8, v134
	v_lshl_or_b32 v132, v3, 12, v2
	s_add_u32 s98, s57, s12
	v_or_b32_e32 v130, 0x40000, v132
	s_addc_u32 s99, s58, s13
	s_mov_b64 s[50:51], -1
	s_andn2_b64 vcc, exec, s[8:9]
	v_cmp_eq_u32_e64 s[12:13], 1, v0
	s_cbranch_vccnz .LBB0_109
	s_cmp_lg_u32 0, -1
	s_cselect_b32 s7, 0, 0
	s_add_i32 s7, s7, s6
	s_add_i32 s20, s7, 0x10000
	s_mov_b32 m0, s20
	s_nop 0
	global_load_lds_dwordx4 v132, s[98:99]
	s_add_i32 s21, s7, 0x12000
	s_mov_b32 m0, s21
	s_nop 0
	global_load_lds_dwordx4 v130, s[98:99]
	s_add_i32 s38, s7, 0x2000
	s_mov_b32 m0, s2
	s_nop 0
	global_load_lds_dwordx4 v132, s[96:97]
	s_add_u32 s8, s98, 0x80000
	s_mov_b32 m0, s38
	s_nop 0
	global_load_lds_dwordx4 v130, s[96:97]
	s_addc_u32 s9, s99, 0
	s_add_i32 s39, s7, 0x14000
	s_mov_b32 m0, s39
	s_nop 0
	global_load_lds_dwordx4 v132, s[8:9]
	s_add_i32 s28, s7, 0x16000
	s_mov_b32 m0, s28
	s_nop 0
	global_load_lds_dwordx4 v130, s[8:9]
	s_add_u32 s8, s96, 0x80000
	s_addc_u32 s9, s97, 0
	s_add_i32 s29, s7, 0x4000
	s_mov_b32 m0, s29
	s_nop 0
	global_load_lds_dwordx4 v132, s[8:9]
	s_add_i32 s62, s7, 0x6000
	s_mov_b32 m0, s62
	s_nop 0
	global_load_lds_dwordx4 v130, s[8:9]
	s_and_saveexec_b64 s[50:51], s[12:13]
	s_cbranch_execz .LBB0_108
	s_barrier
